# K-loop head pointer-select SALU group moved behind the first load segment's ds_read/DMA issue (in-proj, ff1, ff2), on top of loop-edge + v_mov_b64 stack
# baseline (speedup 1.0000x reference)
.LBB0_565:
	s_add_i32 s56, 0, 0x10000
	v_add_u32_e32 v2, s56, v193
	s_add_i32 s58, 0, 0x14000
	ds_read_b128 v[132:135], v2
	ds_read_b128 v[136:139], v2 offset:1024
	ds_read_b128 v[140:143], v2 offset:2048
	ds_read_b128 v[144:147], v2 offset:3072
	v_add_u32_e32 v2, s58, v193
	ds_read_b128 v[148:151], v2
	ds_read_b128 v[152:155], v2 offset:1024
	ds_read_b128 v[156:159], v2 offset:2048
	ds_read_b128 v[160:163], v2 offset:3072
	v_lshl_add_u64 v[236:237], s[6:7], 0, v[188:189]
	s_add_i32 m0, s16, 0xc000
	ds_read_b128 v[164:167], v207
	ds_read_b128 v[208:211], v207 offset:1024
	ds_read_b128 v[212:215], v207 offset:2048
	ds_read_b128 v[216:219], v207 offset:3072
	ds_read_b128 v[220:223], v207 offset:4096
	ds_read_b128 v[224:227], v207 offset:5120
	ds_read_b128 v[228:231], v207 offset:6144
	ds_read_b128 v[232:235], v207 offset:7168
	global_load_lds_dwordx4 v[236:237], off
	v_lshl_add_u64 v[236:237], s[6:7], 0, v[190:191]
	s_add_i32 m0, s16, 0xe000
	s_nop 0
	global_load_lds_dwordx4 v[236:237], off
	s_add_u32 s8, s6, 0xfff80080
	s_addc_u32 s9, s7, -1
	s_cmp_eq_u32 s51, 28
	s_cselect_b32 s11, s28, s9
	s_cselect_b32 s10, s34, s8
	s_cselect_b32 s9, s35, s49
	s_cselect_b32 s8, s44, s45
	s_waitcnt vmcnt(8)
	s_waitcnt lgkmcnt(0)
	s_barrier
	s_waitcnt lgkmcnt(0)
	v_mfma_f32_16x16x32_bf16 v[128:131], v[132:135], v[164:167], v[128:131]
	v_mfma_f32_16x16x32_bf16 v[124:127], v[140:143], v[164:167], v[124:127]
	v_mfma_f32_16x16x32_bf16 v[112:115], v[132:135], v[212:215], v[112:115]
	v_mfma_f32_16x16x32_bf16 v[108:111], v[140:143], v[212:215], v[108:111]
	v_mfma_f32_16x16x32_bf16 v[96:99], v[132:135], v[220:223], v[96:99]
	v_mfma_f32_16x16x32_bf16 v[92:95], v[140:143], v[220:223], v[92:95]
	v_mfma_f32_16x16x32_bf16 v[80:83], v[132:135], v[228:231], v[80:83]
	v_mfma_f32_16x16x32_bf16 v[76:79], v[140:143], v[228:231], v[76:79]
	v_mfma_f32_16x16x32_bf16 v[128:131], v[136:139], v[208:211], v[128:131]
	v_mfma_f32_16x16x32_bf16 v[124:127], v[144:147], v[208:211], v[124:127]
	v_mfma_f32_16x16x32_bf16 v[112:115], v[136:139], v[216:219], v[112:115]
	v_mfma_f32_16x16x32_bf16 v[108:111], v[144:147], v[216:219], v[108:111]
	v_mfma_f32_16x16x32_bf16 v[96:99], v[136:139], v[224:227], v[96:99]
	v_mfma_f32_16x16x32_bf16 v[92:95], v[144:147], v[224:227], v[92:95]
	v_mfma_f32_16x16x32_bf16 v[80:83], v[136:139], v[232:235], v[80:83]
	v_mfma_f32_16x16x32_bf16 v[76:79], v[144:147], v[232:235], v[76:79]
	v_mfma_f32_16x16x32_bf16 v[120:123], v[148:151], v[164:167], v[120:123]
	v_mfma_f32_16x16x32_bf16 v[116:119], v[156:159], v[164:167], v[116:119]
	v_mfma_f32_16x16x32_bf16 v[104:107], v[148:151], v[212:215], v[104:107]
	v_mfma_f32_16x16x32_bf16 v[100:103], v[156:159], v[212:215], v[100:103]
	v_mfma_f32_16x16x32_bf16 v[88:91], v[148:151], v[220:223], v[88:91]
	v_mfma_f32_16x16x32_bf16 v[84:87], v[156:159], v[220:223], v[84:87]
	v_mfma_f32_16x16x32_bf16 v[72:75], v[148:151], v[228:231], v[72:75]
	v_mfma_f32_16x16x32_bf16 v[68:71], v[156:159], v[228:231], v[68:71]
	v_mfma_f32_16x16x32_bf16 v[120:123], v[152:155], v[208:211], v[120:123]
	v_mfma_f32_16x16x32_bf16 v[116:119], v[160:163], v[208:211], v[116:119]
	v_mfma_f32_16x16x32_bf16 v[104:107], v[152:155], v[216:219], v[104:107]
	v_mfma_f32_16x16x32_bf16 v[100:103], v[160:163], v[216:219], v[100:103]
	v_mfma_f32_16x16x32_bf16 v[88:91], v[152:155], v[224:227], v[88:91]
	v_mfma_f32_16x16x32_bf16 v[84:87], v[160:163], v[224:227], v[84:87]
	v_mfma_f32_16x16x32_bf16 v[72:75], v[152:155], v[232:235], v[72:75]
	v_mfma_f32_16x16x32_bf16 v[68:71], v[160:163], v[232:235], v[68:71]
	s_barrier
	s_add_i32 s56, s56, s15
	v_lshl_add_u64 v[236:237], s[8:9], 0, v[184:185]
	s_mov_b32 m0, s56
	ds_read_b128 v[164:167], v207 offset:16384
	ds_read_b128 v[208:211], v207 offset:17408
	ds_read_b128 v[212:215], v207 offset:18432
	ds_read_b128 v[216:219], v207 offset:19456
	ds_read_b128 v[220:223], v207 offset:20480
	ds_read_b128 v[224:227], v207 offset:21504
	ds_read_b128 v[228:231], v207 offset:22528
	ds_read_b128 v[232:235], v207 offset:23552
	global_load_lds_dwordx4 v[236:237], off
	s_add_i32 m0, s56, 0x2000
	s_add_u32 s56, s8, 0x80000
	v_lshl_add_u64 v[238:239], s[8:9], 0, v[180:181]
	s_addc_u32 s57, s9, 0
	s_add_i32 s58, s58, s15
	global_load_lds_dwordx4 v[238:239], off
	v_lshl_add_u64 v[240:241], s[56:57], 0, v[184:185]
	s_mov_b32 m0, s58
	v_lshl_add_u64 v[242:243], s[10:11], 0, v[182:183]
	global_load_lds_dwordx4 v[240:241], off
	v_lshl_add_u64 v[240:241], s[56:57], 0, v[180:181]
	s_add_i32 m0, s58, 0x2000
	s_nop 0
	global_load_lds_dwordx4 v[240:241], off
	v_lshl_add_u64 v[240:241], s[10:11], 0, v[186:187]
	s_mov_b32 m0, s16
	s_nop 0
	global_load_lds_dwordx4 v[240:241], off
	s_mov_b32 m0, s17
	s_nop 0
	global_load_lds_dwordx4 v[242:243], off
	s_waitcnt vmcnt(8)
	s_waitcnt lgkmcnt(0)
	s_barrier
	s_waitcnt lgkmcnt(0)
	v_mfma_f32_16x16x32_bf16 v[64:67], v[132:135], v[164:167], v[64:67]
	v_mfma_f32_16x16x32_bf16 v[60:63], v[140:143], v[164:167], v[60:63]
	v_mfma_f32_16x16x32_bf16 v[48:51], v[132:135], v[212:215], v[48:51]
	v_mfma_f32_16x16x32_bf16 v[44:47], v[140:143], v[212:215], v[44:47]
	v_mfma_f32_16x16x32_bf16 v[32:35], v[132:135], v[220:223], v[32:35]
	v_mfma_f32_16x16x32_bf16 v[28:31], v[140:143], v[220:223], v[28:31]
	v_mfma_f32_16x16x32_bf16 v[16:19], v[132:135], v[228:231], v[16:19]
	v_mfma_f32_16x16x32_bf16 v[12:15], v[140:143], v[228:231], v[12:15]
	v_mfma_f32_16x16x32_bf16 v[64:67], v[136:139], v[208:211], v[64:67]
	v_mfma_f32_16x16x32_bf16 v[60:63], v[144:147], v[208:211], v[60:63]
	v_mfma_f32_16x16x32_bf16 v[48:51], v[136:139], v[216:219], v[48:51]
	v_mfma_f32_16x16x32_bf16 v[44:47], v[144:147], v[216:219], v[44:47]
	v_mfma_f32_16x16x32_bf16 v[32:35], v[136:139], v[224:227], v[32:35]
	v_mfma_f32_16x16x32_bf16 v[28:31], v[144:147], v[224:227], v[28:31]
	v_mfma_f32_16x16x32_bf16 v[16:19], v[136:139], v[232:235], v[16:19]
	v_mfma_f32_16x16x32_bf16 v[12:15], v[144:147], v[232:235], v[12:15]
	v_mfma_f32_16x16x32_bf16 v[56:59], v[148:151], v[164:167], v[56:59]
	v_mfma_f32_16x16x32_bf16 v[52:55], v[156:159], v[164:167], v[52:55]
	v_mfma_f32_16x16x32_bf16 v[40:43], v[148:151], v[212:215], v[40:43]
	v_mfma_f32_16x16x32_bf16 v[36:39], v[156:159], v[212:215], v[36:39]
	v_mfma_f32_16x16x32_bf16 v[24:27], v[148:151], v[220:223], v[24:27]
	v_mfma_f32_16x16x32_bf16 v[20:23], v[156:159], v[220:223], v[20:23]
	v_mfma_f32_16x16x32_bf16 v[8:11], v[148:151], v[228:231], v[8:11]
	v_mfma_f32_16x16x32_bf16 v[4:7], v[156:159], v[228:231], v[4:7]
	v_mfma_f32_16x16x32_bf16 v[56:59], v[152:155], v[208:211], v[56:59]
	v_mfma_f32_16x16x32_bf16 v[52:55], v[160:163], v[208:211], v[52:55]
	v_mfma_f32_16x16x32_bf16 v[40:43], v[152:155], v[216:219], v[40:43]
	v_mfma_f32_16x16x32_bf16 v[36:39], v[160:163], v[216:219], v[36:39]
	v_mfma_f32_16x16x32_bf16 v[24:27], v[152:155], v[224:227], v[24:27]
	v_mfma_f32_16x16x32_bf16 v[20:23], v[160:163], v[224:227], v[20:23]
	v_mfma_f32_16x16x32_bf16 v[8:11], v[152:155], v[232:235], v[8:11]
	v_mfma_f32_16x16x32_bf16 v[4:7], v[160:163], v[232:235], v[4:7]
	s_barrier
	s_add_i32 s56, 0, 0x18000
	v_add_u32_e32 v2, s56, v193
	s_add_i32 s57, 0, 0x1c000
	ds_read_b128 v[132:135], v2
	ds_read_b128 v[136:139], v2 offset:1024
	ds_read_b128 v[140:143], v2 offset:2048
	ds_read_b128 v[144:147], v2 offset:3072
	v_add_u32_e32 v2, s57, v193
	ds_read_b128 v[148:151], v2
	ds_read_b128 v[152:155], v2 offset:1024
	ds_read_b128 v[156:159], v2 offset:2048
	ds_read_b128 v[160:163], v2 offset:3072
	s_add_u32 s10, s10, 0x80000
	s_addc_u32 s11, s11, 0
	s_mov_b32 m0, s18
	v_lshl_add_u64 v[244:245], s[10:11], 0, v[186:187]
	ds_read_b128 v[164:167], v207 offset:32768
	ds_read_b128 v[208:211], v207 offset:33792
	ds_read_b128 v[212:215], v207 offset:34816
	ds_read_b128 v[216:219], v207 offset:35840
	ds_read_b128 v[220:223], v207 offset:36864
	ds_read_b128 v[224:227], v207 offset:37888
	ds_read_b128 v[228:231], v207 offset:38912
	ds_read_b128 v[232:235], v207 offset:39936
	global_load_lds_dwordx4 v[244:245], off
	v_lshl_add_u64 v[244:245], s[10:11], 0, v[182:183]
	s_mov_b32 m0, s19
	s_nop 0
	global_load_lds_dwordx4 v[244:245], off
	s_waitcnt vmcnt(8)
	s_waitcnt lgkmcnt(0)
	s_barrier
	s_waitcnt lgkmcnt(0)
	v_mfma_f32_16x16x32_bf16 v[128:131], v[132:135], v[164:167], v[128:131]
	v_mfma_f32_16x16x32_bf16 v[124:127], v[140:143], v[164:167], v[124:127]
	v_mfma_f32_16x16x32_bf16 v[112:115], v[132:135], v[212:215], v[112:115]
	v_mfma_f32_16x16x32_bf16 v[108:111], v[140:143], v[212:215], v[108:111]
	v_mfma_f32_16x16x32_bf16 v[96:99], v[132:135], v[220:223], v[96:99]
	v_mfma_f32_16x16x32_bf16 v[92:95], v[140:143], v[220:223], v[92:95]
	v_mfma_f32_16x16x32_bf16 v[80:83], v[132:135], v[228:231], v[80:83]
	v_mfma_f32_16x16x32_bf16 v[76:79], v[140:143], v[228:231], v[76:79]
	v_mfma_f32_16x16x32_bf16 v[128:131], v[136:139], v[208:211], v[128:131]
	v_mfma_f32_16x16x32_bf16 v[124:127], v[144:147], v[208:211], v[124:127]
	v_mfma_f32_16x16x32_bf16 v[112:115], v[136:139], v[216:219], v[112:115]
	v_mfma_f32_16x16x32_bf16 v[108:111], v[144:147], v[216:219], v[108:111]
	v_mfma_f32_16x16x32_bf16 v[96:99], v[136:139], v[224:227], v[96:99]
	v_mfma_f32_16x16x32_bf16 v[92:95], v[144:147], v[224:227], v[92:95]
	v_mfma_f32_16x16x32_bf16 v[80:83], v[136:139], v[232:235], v[80:83]
	v_mfma_f32_16x16x32_bf16 v[76:79], v[144:147], v[232:235], v[76:79]
	v_mfma_f32_16x16x32_bf16 v[120:123], v[148:151], v[164:167], v[120:123]
	v_mfma_f32_16x16x32_bf16 v[116:119], v[156:159], v[164:167], v[116:119]
	v_mfma_f32_16x16x32_bf16 v[104:107], v[148:151], v[212:215], v[104:107]
	v_mfma_f32_16x16x32_bf16 v[100:103], v[156:159], v[212:215], v[100:103]
	v_mfma_f32_16x16x32_bf16 v[88:91], v[148:151], v[220:223], v[88:91]
	v_mfma_f32_16x16x32_bf16 v[84:87], v[156:159], v[220:223], v[84:87]
	v_mfma_f32_16x16x32_bf16 v[72:75], v[148:151], v[228:231], v[72:75]
	v_mfma_f32_16x16x32_bf16 v[68:71], v[156:159], v[228:231], v[68:71]
	v_mfma_f32_16x16x32_bf16 v[120:123], v[152:155], v[208:211], v[120:123]
	v_mfma_f32_16x16x32_bf16 v[116:119], v[160:163], v[208:211], v[116:119]
	v_mfma_f32_16x16x32_bf16 v[104:107], v[152:155], v[216:219], v[104:107]
	v_mfma_f32_16x16x32_bf16 v[100:103], v[160:163], v[216:219], v[100:103]
	v_mfma_f32_16x16x32_bf16 v[88:91], v[152:155], v[224:227], v[88:91]
	v_mfma_f32_16x16x32_bf16 v[84:87], v[160:163], v[224:227], v[84:87]
	v_mfma_f32_16x16x32_bf16 v[72:75], v[152:155], v[232:235], v[72:75]
	v_mfma_f32_16x16x32_bf16 v[68:71], v[160:163], v[232:235], v[68:71]
	s_barrier
	s_add_i32 s10, s56, s15
	v_lshl_add_u64 v[236:237], v[236:237], 0, s[2:3]
	s_mov_b32 m0, s10
	ds_read_b128 v[164:167], v207 offset:49152
	ds_read_b128 v[208:211], v207 offset:50176
	ds_read_b128 v[212:215], v207 offset:51200
	ds_read_b128 v[216:219], v207 offset:52224
	ds_read_b128 v[220:223], v207 offset:53248
	ds_read_b128 v[224:227], v207 offset:54272
	ds_read_b128 v[228:231], v207 offset:55296
	ds_read_b128 v[232:235], v207 offset:56320
	global_load_lds_dwordx4 v[236:237], off
	s_add_i32 m0, s10, 0x2000
	s_add_u32 s8, s8, 0x80080
	v_lshl_add_u64 v[236:237], v[238:239], 0, s[2:3]
	s_addc_u32 s9, s9, 0
	s_add_i32 s10, s57, s15
	global_load_lds_dwordx4 v[236:237], off
	v_lshl_add_u64 v[236:237], s[8:9], 0, v[184:185]
	s_mov_b32 m0, s10
	s_nop 0
	global_load_lds_dwordx4 v[236:237], off
	v_lshl_add_u64 v[236:237], s[8:9], 0, v[180:181]
	s_add_i32 m0, s10, 0x2000
	s_nop 0
	global_load_lds_dwordx4 v[236:237], off
	v_lshl_add_u64 v[236:237], v[240:241], 0, s[2:3]
	s_mov_b32 m0, s20
	s_nop 0
	global_load_lds_dwordx4 v[236:237], off
	v_lshl_add_u64 v[236:237], v[242:243], 0, s[2:3]
	s_mov_b32 m0, s21
	s_nop 0
	global_load_lds_dwordx4 v[236:237], off
	s_add_i32 s51, s51, 2
	s_add_u32 s6, s6, 0x100
	s_addc_u32 s7, s7, 0
	s_add_u32 s45, s45, 0x100
	s_addc_u32 s49, s49, 0
	s_cmp_gt_u32 s51, 29
	s_waitcnt vmcnt(8)
	s_waitcnt lgkmcnt(0)
	s_barrier
	s_waitcnt lgkmcnt(0)
	v_mfma_f32_16x16x32_bf16 v[64:67], v[132:135], v[164:167], v[64:67]
	v_mfma_f32_16x16x32_bf16 v[60:63], v[140:143], v[164:167], v[60:63]
	v_mfma_f32_16x16x32_bf16 v[48:51], v[132:135], v[212:215], v[48:51]
	v_mfma_f32_16x16x32_bf16 v[44:47], v[140:143], v[212:215], v[44:47]
	v_mfma_f32_16x16x32_bf16 v[32:35], v[132:135], v[220:223], v[32:35]
	v_mfma_f32_16x16x32_bf16 v[28:31], v[140:143], v[220:223], v[28:31]
	v_mfma_f32_16x16x32_bf16 v[16:19], v[132:135], v[228:231], v[16:19]
	v_mfma_f32_16x16x32_bf16 v[12:15], v[140:143], v[228:231], v[12:15]
	v_mfma_f32_16x16x32_bf16 v[64:67], v[136:139], v[208:211], v[64:67]
	v_mfma_f32_16x16x32_bf16 v[60:63], v[144:147], v[208:211], v[60:63]
	v_mfma_f32_16x16x32_bf16 v[48:51], v[136:139], v[216:219], v[48:51]
	v_mfma_f32_16x16x32_bf16 v[44:47], v[144:147], v[216:219], v[44:47]
	v_mfma_f32_16x16x32_bf16 v[32:35], v[136:139], v[224:227], v[32:35]
	v_mfma_f32_16x16x32_bf16 v[28:31], v[144:147], v[224:227], v[28:31]
	v_mfma_f32_16x16x32_bf16 v[16:19], v[136:139], v[232:235], v[16:19]
	v_mfma_f32_16x16x32_bf16 v[12:15], v[144:147], v[232:235], v[12:15]
	v_mfma_f32_16x16x32_bf16 v[56:59], v[148:151], v[164:167], v[56:59]
	v_mfma_f32_16x16x32_bf16 v[52:55], v[156:159], v[164:167], v[52:55]
	v_mfma_f32_16x16x32_bf16 v[40:43], v[148:151], v[212:215], v[40:43]
	v_mfma_f32_16x16x32_bf16 v[36:39], v[156:159], v[212:215], v[36:39]
	v_mfma_f32_16x16x32_bf16 v[24:27], v[148:151], v[220:223], v[24:27]
	v_mfma_f32_16x16x32_bf16 v[20:23], v[156:159], v[220:223], v[20:23]
	v_mfma_f32_16x16x32_bf16 v[8:11], v[148:151], v[228:231], v[8:11]
	v_mfma_f32_16x16x32_bf16 v[4:7], v[156:159], v[228:231], v[4:7]
	v_mfma_f32_16x16x32_bf16 v[56:59], v[152:155], v[208:211], v[56:59]
	v_mfma_f32_16x16x32_bf16 v[52:55], v[160:163], v[208:211], v[52:55]
	v_mfma_f32_16x16x32_bf16 v[40:43], v[152:155], v[216:219], v[40:43]
	v_mfma_f32_16x16x32_bf16 v[36:39], v[160:163], v[216:219], v[36:39]
	v_mfma_f32_16x16x32_bf16 v[24:27], v[152:155], v[224:227], v[24:27]
	v_mfma_f32_16x16x32_bf16 v[20:23], v[160:163], v[224:227], v[20:23]
	v_mfma_f32_16x16x32_bf16 v[8:11], v[152:155], v[232:235], v[8:11]
	v_mfma_f32_16x16x32_bf16 v[4:7], v[160:163], v[232:235], v[4:7]
	s_barrier
	s_cbranch_scc0 .LBB0_565
	s_and_b64 vcc, exec, s[46:47]
	s_cbranch_vccz .LBB0_568
	s_barrier

.LBB0_1222:
	s_add_i32 s54, 0, 0x10000
	v_add_u32_e32 v142, s54, v144
	s_add_i32 s56, 0, 0x14000
	ds_read_b128 v[148:151], v142
	ds_read_b128 v[152:155], v142 offset:1024
	ds_read_b128 v[156:159], v142 offset:2048
	ds_read_b128 v[160:163], v142 offset:3072
	v_add_u32_e32 v142, s56, v144
	ds_read_b128 v[164:167], v142
	ds_read_b128 v[180:183], v142 offset:1024
	ds_read_b128 v[184:187], v142 offset:2048
	ds_read_b128 v[188:191], v142 offset:3072
	v_lshl_add_u64 v[142:143], s[18:19], 0, v[138:139]
	s_add_i32 m0, s34, 0xc000
	ds_read_b128 v[192:195], v146
	ds_read_b128 v[196:199], v146 offset:1024
	ds_read_b128 v[208:211], v146 offset:2048
	ds_read_b128 v[212:215], v146 offset:3072
	ds_read_b128 v[216:219], v146 offset:4096
	ds_read_b128 v[220:223], v146 offset:5120
	ds_read_b128 v[224:227], v146 offset:6144
	ds_read_b128 v[228:231], v146 offset:7168
	global_load_lds_dwordx4 v[142:143], off
	v_lshl_add_u64 v[142:143], s[18:19], 0, v[140:141]
	s_add_i32 m0, s34, 0xe000
	s_nop 0
	global_load_lds_dwordx4 v[142:143], off
	s_add_u32 s20, s18, 0xfff80080
	s_addc_u32 s21, s19, -1
	s_cmp_eq_u32 s53, 28
	s_cselect_b32 s25, s13, s21
	s_cselect_b32 s24, s49, s20
	s_cselect_b32 s21, s11, s52
	s_cselect_b32 s20, s50, s51
	s_waitcnt vmcnt(8)
	s_waitcnt lgkmcnt(0)
	s_barrier
	s_waitcnt lgkmcnt(0)
	v_mfma_f32_16x16x32_bf16 v[128:131], v[148:151], v[192:195], v[128:131]
	v_mfma_f32_16x16x32_bf16 v[124:127], v[156:159], v[192:195], v[124:127]
	v_mfma_f32_16x16x32_bf16 v[112:115], v[148:151], v[208:211], v[112:115]
	v_mfma_f32_16x16x32_bf16 v[108:111], v[156:159], v[208:211], v[108:111]
	v_mfma_f32_16x16x32_bf16 v[96:99], v[148:151], v[216:219], v[96:99]
	v_mfma_f32_16x16x32_bf16 v[92:95], v[156:159], v[216:219], v[92:95]
	v_mfma_f32_16x16x32_bf16 v[80:83], v[148:151], v[224:227], v[80:83]
	v_mfma_f32_16x16x32_bf16 v[76:79], v[156:159], v[224:227], v[76:79]
	v_mfma_f32_16x16x32_bf16 v[128:131], v[152:155], v[196:199], v[128:131]
	v_mfma_f32_16x16x32_bf16 v[124:127], v[160:163], v[196:199], v[124:127]
	v_mfma_f32_16x16x32_bf16 v[112:115], v[152:155], v[212:215], v[112:115]
	v_mfma_f32_16x16x32_bf16 v[108:111], v[160:163], v[212:215], v[108:111]
	v_mfma_f32_16x16x32_bf16 v[96:99], v[152:155], v[220:223], v[96:99]
	v_mfma_f32_16x16x32_bf16 v[92:95], v[160:163], v[220:223], v[92:95]
	v_mfma_f32_16x16x32_bf16 v[80:83], v[152:155], v[228:231], v[80:83]
	v_mfma_f32_16x16x32_bf16 v[76:79], v[160:163], v[228:231], v[76:79]
	v_mfma_f32_16x16x32_bf16 v[120:123], v[164:167], v[192:195], v[120:123]
	v_mfma_f32_16x16x32_bf16 v[116:119], v[184:187], v[192:195], v[116:119]
	v_mfma_f32_16x16x32_bf16 v[104:107], v[164:167], v[208:211], v[104:107]
	v_mfma_f32_16x16x32_bf16 v[100:103], v[184:187], v[208:211], v[100:103]
	v_mfma_f32_16x16x32_bf16 v[88:91], v[164:167], v[216:219], v[88:91]
	v_mfma_f32_16x16x32_bf16 v[84:87], v[184:187], v[216:219], v[84:87]
	v_mfma_f32_16x16x32_bf16 v[72:75], v[164:167], v[224:227], v[72:75]
	v_mfma_f32_16x16x32_bf16 v[68:71], v[184:187], v[224:227], v[68:71]
	v_mfma_f32_16x16x32_bf16 v[120:123], v[180:183], v[196:199], v[120:123]
	v_mfma_f32_16x16x32_bf16 v[116:119], v[188:191], v[196:199], v[116:119]
	v_mfma_f32_16x16x32_bf16 v[104:107], v[180:183], v[212:215], v[104:107]
	v_mfma_f32_16x16x32_bf16 v[100:103], v[188:191], v[212:215], v[100:103]
	v_mfma_f32_16x16x32_bf16 v[88:91], v[180:183], v[220:223], v[88:91]
	v_mfma_f32_16x16x32_bf16 v[84:87], v[188:191], v[220:223], v[84:87]
	v_mfma_f32_16x16x32_bf16 v[72:75], v[180:183], v[228:231], v[72:75]
	v_mfma_f32_16x16x32_bf16 v[68:71], v[188:191], v[228:231], v[68:71]
	s_barrier
	s_add_i32 s54, s54, s28
	v_lshl_add_u64 v[142:143], s[20:21], 0, v[2:3]
	s_mov_b32 m0, s54
	ds_read_b128 v[192:195], v146 offset:16384
	ds_read_b128 v[196:199], v146 offset:17408
	ds_read_b128 v[208:211], v146 offset:18432
	ds_read_b128 v[212:215], v146 offset:19456
	ds_read_b128 v[216:219], v146 offset:20480
	ds_read_b128 v[220:223], v146 offset:21504
	ds_read_b128 v[224:227], v146 offset:22528
	ds_read_b128 v[228:231], v146 offset:23552
	global_load_lds_dwordx4 v[142:143], off
	s_add_i32 m0, s54, 0x2000
	s_add_u32 s54, s20, 0x80000
	v_lshl_add_u64 v[232:233], s[20:21], 0, v[132:133]
	s_addc_u32 s55, s21, 0
	s_add_i32 s56, s56, s28
	global_load_lds_dwordx4 v[232:233], off
	v_lshl_add_u64 v[234:235], s[54:55], 0, v[2:3]
	s_mov_b32 m0, s56
	v_lshl_add_u64 v[236:237], s[24:25], 0, v[134:135]
	global_load_lds_dwordx4 v[234:235], off
	v_lshl_add_u64 v[234:235], s[54:55], 0, v[132:133]
	s_add_i32 m0, s56, 0x2000
	s_nop 0
	global_load_lds_dwordx4 v[234:235], off
	v_lshl_add_u64 v[234:235], s[24:25], 0, v[136:137]
	s_mov_b32 m0, s34
	s_nop 0
	global_load_lds_dwordx4 v[234:235], off
	s_mov_b32 m0, s35
	s_nop 0
	global_load_lds_dwordx4 v[236:237], off
	s_waitcnt vmcnt(8)
	s_waitcnt lgkmcnt(0)
	s_barrier
	s_waitcnt lgkmcnt(0)
	v_mfma_f32_16x16x32_bf16 v[64:67], v[148:151], v[192:195], v[64:67]
	v_mfma_f32_16x16x32_bf16 v[60:63], v[156:159], v[192:195], v[60:63]
	v_mfma_f32_16x16x32_bf16 v[48:51], v[148:151], v[208:211], v[48:51]
	v_mfma_f32_16x16x32_bf16 v[44:47], v[156:159], v[208:211], v[44:47]
	v_mfma_f32_16x16x32_bf16 v[32:35], v[148:151], v[216:219], v[32:35]
	v_mfma_f32_16x16x32_bf16 v[28:31], v[156:159], v[216:219], v[28:31]
	v_mfma_f32_16x16x32_bf16 v[16:19], v[148:151], v[224:227], v[16:19]
	v_mfma_f32_16x16x32_bf16 v[12:15], v[156:159], v[224:227], v[12:15]
	v_mfma_f32_16x16x32_bf16 v[64:67], v[152:155], v[196:199], v[64:67]
	v_mfma_f32_16x16x32_bf16 v[60:63], v[160:163], v[196:199], v[60:63]
	v_mfma_f32_16x16x32_bf16 v[48:51], v[152:155], v[212:215], v[48:51]
	v_mfma_f32_16x16x32_bf16 v[44:47], v[160:163], v[212:215], v[44:47]
	v_mfma_f32_16x16x32_bf16 v[32:35], v[152:155], v[220:223], v[32:35]
	v_mfma_f32_16x16x32_bf16 v[28:31], v[160:163], v[220:223], v[28:31]
	v_mfma_f32_16x16x32_bf16 v[16:19], v[152:155], v[228:231], v[16:19]
	v_mfma_f32_16x16x32_bf16 v[12:15], v[160:163], v[228:231], v[12:15]
	v_mfma_f32_16x16x32_bf16 v[56:59], v[164:167], v[192:195], v[56:59]
	v_mfma_f32_16x16x32_bf16 v[52:55], v[184:187], v[192:195], v[52:55]
	v_mfma_f32_16x16x32_bf16 v[40:43], v[164:167], v[208:211], v[40:43]
	v_mfma_f32_16x16x32_bf16 v[36:39], v[184:187], v[208:211], v[36:39]
	v_mfma_f32_16x16x32_bf16 v[24:27], v[164:167], v[216:219], v[24:27]
	v_mfma_f32_16x16x32_bf16 v[20:23], v[184:187], v[216:219], v[20:23]
	v_mfma_f32_16x16x32_bf16 v[8:11], v[164:167], v[224:227], v[8:11]
	v_mfma_f32_16x16x32_bf16 v[4:7], v[184:187], v[224:227], v[4:7]
	v_mfma_f32_16x16x32_bf16 v[56:59], v[180:183], v[196:199], v[56:59]
	v_mfma_f32_16x16x32_bf16 v[52:55], v[188:191], v[196:199], v[52:55]
	v_mfma_f32_16x16x32_bf16 v[40:43], v[180:183], v[212:215], v[40:43]
	v_mfma_f32_16x16x32_bf16 v[36:39], v[188:191], v[212:215], v[36:39]
	v_mfma_f32_16x16x32_bf16 v[24:27], v[180:183], v[220:223], v[24:27]
	v_mfma_f32_16x16x32_bf16 v[20:23], v[188:191], v[220:223], v[20:23]
	v_mfma_f32_16x16x32_bf16 v[8:11], v[180:183], v[228:231], v[8:11]
	v_mfma_f32_16x16x32_bf16 v[4:7], v[188:191], v[228:231], v[4:7]
	s_barrier
	s_add_i32 s54, 0, 0x18000
	v_add_u32_e32 v147, s54, v144
	s_add_i32 s55, 0, 0x1c000
	ds_read_b128 v[148:151], v147
	ds_read_b128 v[152:155], v147 offset:1024
	ds_read_b128 v[156:159], v147 offset:2048
	ds_read_b128 v[160:163], v147 offset:3072
	v_add_u32_e32 v147, s55, v144
	ds_read_b128 v[164:167], v147
	ds_read_b128 v[180:183], v147 offset:1024
	ds_read_b128 v[184:187], v147 offset:2048
	ds_read_b128 v[188:191], v147 offset:3072
	s_add_u32 s24, s24, 0x80000
	s_addc_u32 s25, s25, 0
	s_mov_b32 m0, s42
	v_lshl_add_u64 v[238:239], s[24:25], 0, v[136:137]
	ds_read_b128 v[192:195], v146 offset:32768
	ds_read_b128 v[196:199], v146 offset:33792
	ds_read_b128 v[208:211], v146 offset:34816
	ds_read_b128 v[212:215], v146 offset:35840
	ds_read_b128 v[216:219], v146 offset:36864
	ds_read_b128 v[220:223], v146 offset:37888
	ds_read_b128 v[224:227], v146 offset:38912
	ds_read_b128 v[228:231], v146 offset:39936
	global_load_lds_dwordx4 v[238:239], off
	v_lshl_add_u64 v[238:239], s[24:25], 0, v[134:135]
	s_mov_b32 m0, s43
	s_nop 0
	global_load_lds_dwordx4 v[238:239], off
	s_waitcnt vmcnt(8)
	s_waitcnt lgkmcnt(0)
	s_barrier
	s_waitcnt lgkmcnt(0)
	v_mfma_f32_16x16x32_bf16 v[128:131], v[148:151], v[192:195], v[128:131]
	v_mfma_f32_16x16x32_bf16 v[124:127], v[156:159], v[192:195], v[124:127]
	v_mfma_f32_16x16x32_bf16 v[112:115], v[148:151], v[208:211], v[112:115]
	v_mfma_f32_16x16x32_bf16 v[108:111], v[156:159], v[208:211], v[108:111]
	v_mfma_f32_16x16x32_bf16 v[96:99], v[148:151], v[216:219], v[96:99]
	v_mfma_f32_16x16x32_bf16 v[92:95], v[156:159], v[216:219], v[92:95]
	v_mfma_f32_16x16x32_bf16 v[80:83], v[148:151], v[224:227], v[80:83]
	v_mfma_f32_16x16x32_bf16 v[76:79], v[156:159], v[224:227], v[76:79]
	v_mfma_f32_16x16x32_bf16 v[128:131], v[152:155], v[196:199], v[128:131]
	v_mfma_f32_16x16x32_bf16 v[124:127], v[160:163], v[196:199], v[124:127]
	v_mfma_f32_16x16x32_bf16 v[112:115], v[152:155], v[212:215], v[112:115]
	v_mfma_f32_16x16x32_bf16 v[108:111], v[160:163], v[212:215], v[108:111]
	v_mfma_f32_16x16x32_bf16 v[96:99], v[152:155], v[220:223], v[96:99]
	v_mfma_f32_16x16x32_bf16 v[92:95], v[160:163], v[220:223], v[92:95]
	v_mfma_f32_16x16x32_bf16 v[80:83], v[152:155], v[228:231], v[80:83]
	v_mfma_f32_16x16x32_bf16 v[76:79], v[160:163], v[228:231], v[76:79]
	v_mfma_f32_16x16x32_bf16 v[120:123], v[164:167], v[192:195], v[120:123]
	v_mfma_f32_16x16x32_bf16 v[116:119], v[184:187], v[192:195], v[116:119]
	v_mfma_f32_16x16x32_bf16 v[104:107], v[164:167], v[208:211], v[104:107]
	v_mfma_f32_16x16x32_bf16 v[100:103], v[184:187], v[208:211], v[100:103]
	v_mfma_f32_16x16x32_bf16 v[88:91], v[164:167], v[216:219], v[88:91]
	v_mfma_f32_16x16x32_bf16 v[84:87], v[184:187], v[216:219], v[84:87]
	v_mfma_f32_16x16x32_bf16 v[72:75], v[164:167], v[224:227], v[72:75]
	v_mfma_f32_16x16x32_bf16 v[68:71], v[184:187], v[224:227], v[68:71]
	v_mfma_f32_16x16x32_bf16 v[120:123], v[180:183], v[196:199], v[120:123]
	v_mfma_f32_16x16x32_bf16 v[116:119], v[188:191], v[196:199], v[116:119]
	v_mfma_f32_16x16x32_bf16 v[104:107], v[180:183], v[212:215], v[104:107]
	v_mfma_f32_16x16x32_bf16 v[100:103], v[188:191], v[212:215], v[100:103]
	v_mfma_f32_16x16x32_bf16 v[88:91], v[180:183], v[220:223], v[88:91]
	v_mfma_f32_16x16x32_bf16 v[84:87], v[188:191], v[220:223], v[84:87]
	v_mfma_f32_16x16x32_bf16 v[72:75], v[180:183], v[228:231], v[72:75]
	v_mfma_f32_16x16x32_bf16 v[68:71], v[188:191], v[228:231], v[68:71]
	s_barrier
	s_add_i32 s24, s54, s28
	v_lshl_add_u64 v[142:143], v[142:143], 0, s[2:3]
	s_mov_b32 m0, s24
	ds_read_b128 v[192:195], v146 offset:49152
	ds_read_b128 v[196:199], v146 offset:50176
	ds_read_b128 v[208:211], v146 offset:51200
	ds_read_b128 v[212:215], v146 offset:52224
	ds_read_b128 v[216:219], v146 offset:53248
	ds_read_b128 v[220:223], v146 offset:54272
	ds_read_b128 v[224:227], v146 offset:55296
	ds_read_b128 v[228:231], v146 offset:56320
	global_load_lds_dwordx4 v[142:143], off
	s_add_i32 m0, s24, 0x2000
	s_add_u32 s20, s20, 0x80080
	v_lshl_add_u64 v[142:143], v[232:233], 0, s[2:3]
	s_addc_u32 s21, s21, 0
	s_add_i32 s24, s55, s28
	global_load_lds_dwordx4 v[142:143], off
	v_lshl_add_u64 v[142:143], s[20:21], 0, v[2:3]
	s_mov_b32 m0, s24
	s_nop 0
	global_load_lds_dwordx4 v[142:143], off
	v_lshl_add_u64 v[142:143], s[20:21], 0, v[132:133]
	s_add_i32 m0, s24, 0x2000
	s_nop 0
	global_load_lds_dwordx4 v[142:143], off
	v_lshl_add_u64 v[142:143], v[234:235], 0, s[2:3]
	s_mov_b32 m0, s44
	s_nop 0
	global_load_lds_dwordx4 v[142:143], off
	v_lshl_add_u64 v[142:143], v[236:237], 0, s[2:3]
	s_mov_b32 m0, s45
	s_nop 0
	global_load_lds_dwordx4 v[142:143], off
	s_add_i32 s53, s53, 2
	s_add_u32 s18, s18, 0x100
	s_addc_u32 s19, s19, 0
	s_add_u32 s51, s51, 0x100
	s_addc_u32 s52, s52, 0
	s_cmp_gt_u32 s53, 29
	s_waitcnt vmcnt(8)
	s_waitcnt lgkmcnt(0)
	s_barrier
	s_waitcnt lgkmcnt(0)
	v_mfma_f32_16x16x32_bf16 v[64:67], v[148:151], v[192:195], v[64:67]
	v_mfma_f32_16x16x32_bf16 v[60:63], v[156:159], v[192:195], v[60:63]
	v_mfma_f32_16x16x32_bf16 v[48:51], v[148:151], v[208:211], v[48:51]
	v_mfma_f32_16x16x32_bf16 v[44:47], v[156:159], v[208:211], v[44:47]
	v_mfma_f32_16x16x32_bf16 v[32:35], v[148:151], v[216:219], v[32:35]
	v_mfma_f32_16x16x32_bf16 v[28:31], v[156:159], v[216:219], v[28:31]
	v_mfma_f32_16x16x32_bf16 v[16:19], v[148:151], v[224:227], v[16:19]
	v_mfma_f32_16x16x32_bf16 v[12:15], v[156:159], v[224:227], v[12:15]
	v_mfma_f32_16x16x32_bf16 v[64:67], v[152:155], v[196:199], v[64:67]
	v_mfma_f32_16x16x32_bf16 v[60:63], v[160:163], v[196:199], v[60:63]
	v_mfma_f32_16x16x32_bf16 v[48:51], v[152:155], v[212:215], v[48:51]
	v_mfma_f32_16x16x32_bf16 v[44:47], v[160:163], v[212:215], v[44:47]
	v_mfma_f32_16x16x32_bf16 v[32:35], v[152:155], v[220:223], v[32:35]
	v_mfma_f32_16x16x32_bf16 v[28:31], v[160:163], v[220:223], v[28:31]
	v_mfma_f32_16x16x32_bf16 v[16:19], v[152:155], v[228:231], v[16:19]
	v_mfma_f32_16x16x32_bf16 v[12:15], v[160:163], v[228:231], v[12:15]
	v_mfma_f32_16x16x32_bf16 v[56:59], v[164:167], v[192:195], v[56:59]
	v_mfma_f32_16x16x32_bf16 v[52:55], v[184:187], v[192:195], v[52:55]
	v_mfma_f32_16x16x32_bf16 v[40:43], v[164:167], v[208:211], v[40:43]
	v_mfma_f32_16x16x32_bf16 v[36:39], v[184:187], v[208:211], v[36:39]
	v_mfma_f32_16x16x32_bf16 v[24:27], v[164:167], v[216:219], v[24:27]
	v_mfma_f32_16x16x32_bf16 v[20:23], v[184:187], v[216:219], v[20:23]
	v_mfma_f32_16x16x32_bf16 v[8:11], v[164:167], v[224:227], v[8:11]
	v_mfma_f32_16x16x32_bf16 v[4:7], v[184:187], v[224:227], v[4:7]
	v_mfma_f32_16x16x32_bf16 v[56:59], v[180:183], v[196:199], v[56:59]
	v_mfma_f32_16x16x32_bf16 v[52:55], v[188:191], v[196:199], v[52:55]
	v_mfma_f32_16x16x32_bf16 v[40:43], v[180:183], v[212:215], v[40:43]
	v_mfma_f32_16x16x32_bf16 v[36:39], v[188:191], v[212:215], v[36:39]
	v_mfma_f32_16x16x32_bf16 v[24:27], v[180:183], v[220:223], v[24:27]
	v_mfma_f32_16x16x32_bf16 v[20:23], v[188:191], v[220:223], v[20:23]
	v_mfma_f32_16x16x32_bf16 v[8:11], v[180:183], v[228:231], v[8:11]
	v_mfma_f32_16x16x32_bf16 v[4:7], v[188:191], v[228:231], v[4:7]
	s_barrier
	s_cbranch_scc0 .LBB0_1222
	s_and_b64 vcc, exec, s[8:9]
	s_cbranch_vccz .LBB0_1225
	s_barrier

.LBB0_1295:
	s_add_i32 s55, 0, 0x10000
	v_add_u32_e32 v2, s55, v1
	s_add_i32 s58, 0, 0x14000
	ds_read_b128 v[146:149], v2
	ds_read_b128 v[150:153], v2 offset:1024
	ds_read_b128 v[154:157], v2 offset:2048
	ds_read_b128 v[158:161], v2 offset:3072
	v_add_u32_e32 v2, s58, v1
	ds_read_b128 v[162:165], v2
	ds_read_b128 v[180:183], v2 offset:1024
	ds_read_b128 v[184:187], v2 offset:2048
	ds_read_b128 v[188:191], v2 offset:3072
	v_lshl_add_u64 v[166:167], s[20:21], 0, v[140:141]
	s_add_i32 m0, s40, 0xc000
	ds_read_b128 v[192:195], v145
	ds_read_b128 v[196:199], v145 offset:1024
	ds_read_b128 v[208:211], v145 offset:2048
	ds_read_b128 v[212:215], v145 offset:3072
	ds_read_b128 v[216:219], v145 offset:4096
	ds_read_b128 v[220:223], v145 offset:5120
	ds_read_b128 v[224:227], v145 offset:6144
	ds_read_b128 v[228:231], v145 offset:7168
	global_load_lds_dwordx4 v[166:167], off
	v_lshl_add_u64 v[166:167], s[20:21], 0, v[142:143]
	s_add_i32 m0, s40, 0xe000
	s_nop 0
	global_load_lds_dwordx4 v[166:167], off
	s_add_i32 s54, s24, 2
	s_add_u32 s25, s20, 0xffe00080
	s_addc_u32 s26, s21, -1
	s_cmp_eq_u32 s11, s24
	s_cselect_b32 s27, s13, s26
	s_cselect_b32 s26, s12, s25
	s_cselect_b32 s25, s19, s53
	s_cselect_b32 s24, s18, s17
	s_waitcnt vmcnt(8)
	s_waitcnt lgkmcnt(0)
	s_barrier
	s_waitcnt lgkmcnt(0)
	v_mfma_f32_16x16x32_bf16 v[128:131], v[146:149], v[192:195], v[128:131]
	v_mfma_f32_16x16x32_bf16 v[124:127], v[154:157], v[192:195], v[124:127]
	v_mfma_f32_16x16x32_bf16 v[120:123], v[146:149], v[208:211], v[120:123]
	v_mfma_f32_16x16x32_bf16 v[112:115], v[154:157], v[208:211], v[112:115]
	v_mfma_f32_16x16x32_bf16 v[104:107], v[146:149], v[216:219], v[104:107]
	v_mfma_f32_16x16x32_bf16 v[96:99], v[154:157], v[216:219], v[96:99]
	v_mfma_f32_16x16x32_bf16 v[88:91], v[146:149], v[224:227], v[88:91]
	v_mfma_f32_16x16x32_bf16 v[80:83], v[154:157], v[224:227], v[80:83]
	v_mfma_f32_16x16x32_bf16 v[128:131], v[150:153], v[196:199], v[128:131]
	v_mfma_f32_16x16x32_bf16 v[124:127], v[158:161], v[196:199], v[124:127]
	v_mfma_f32_16x16x32_bf16 v[120:123], v[150:153], v[212:215], v[120:123]
	v_mfma_f32_16x16x32_bf16 v[112:115], v[158:161], v[212:215], v[112:115]
	v_mfma_f32_16x16x32_bf16 v[104:107], v[150:153], v[220:223], v[104:107]
	v_mfma_f32_16x16x32_bf16 v[96:99], v[158:161], v[220:223], v[96:99]
	v_mfma_f32_16x16x32_bf16 v[88:91], v[150:153], v[228:231], v[88:91]
	v_mfma_f32_16x16x32_bf16 v[80:83], v[158:161], v[228:231], v[80:83]
	v_mfma_f32_16x16x32_bf16 v[116:119], v[162:165], v[192:195], v[116:119]
	v_mfma_f32_16x16x32_bf16 v[108:111], v[184:187], v[192:195], v[108:111]
	v_mfma_f32_16x16x32_bf16 v[100:103], v[162:165], v[208:211], v[100:103]
	v_mfma_f32_16x16x32_bf16 v[92:95], v[184:187], v[208:211], v[92:95]
	v_mfma_f32_16x16x32_bf16 v[84:87], v[162:165], v[216:219], v[84:87]
	v_mfma_f32_16x16x32_bf16 v[76:79], v[184:187], v[216:219], v[76:79]
	v_mfma_f32_16x16x32_bf16 v[72:75], v[162:165], v[224:227], v[72:75]
	v_mfma_f32_16x16x32_bf16 v[68:71], v[184:187], v[224:227], v[68:71]
	v_mfma_f32_16x16x32_bf16 v[116:119], v[180:183], v[196:199], v[116:119]
	v_mfma_f32_16x16x32_bf16 v[108:111], v[188:191], v[196:199], v[108:111]
	v_mfma_f32_16x16x32_bf16 v[100:103], v[180:183], v[212:215], v[100:103]
	v_mfma_f32_16x16x32_bf16 v[92:95], v[188:191], v[212:215], v[92:95]
	v_mfma_f32_16x16x32_bf16 v[84:87], v[180:183], v[220:223], v[84:87]
	v_mfma_f32_16x16x32_bf16 v[76:79], v[188:191], v[220:223], v[76:79]
	v_mfma_f32_16x16x32_bf16 v[72:75], v[180:183], v[228:231], v[72:75]
	v_mfma_f32_16x16x32_bf16 v[68:71], v[188:191], v[228:231], v[68:71]
	s_barrier
	s_add_i32 s55, s55, s35
	v_lshl_add_u64 v[166:167], s[24:25], 0, v[136:137]
	s_mov_b32 m0, s55
	ds_read_b128 v[192:195], v145 offset:16384
	ds_read_b128 v[196:199], v145 offset:17408
	ds_read_b128 v[208:211], v145 offset:18432
	ds_read_b128 v[212:215], v145 offset:19456
	ds_read_b128 v[216:219], v145 offset:20480
	ds_read_b128 v[220:223], v145 offset:21504
	ds_read_b128 v[224:227], v145 offset:22528
	ds_read_b128 v[228:231], v145 offset:23552
	global_load_lds_dwordx4 v[166:167], off
	s_add_i32 m0, s55, 0x2000
	s_add_u32 s56, s24, 0x200000
	v_lshl_add_u64 v[232:233], s[24:25], 0, v[132:133]
	s_addc_u32 s57, s25, 0
	s_add_i32 s55, s58, s35
	global_load_lds_dwordx4 v[232:233], off
	v_lshl_add_u64 v[234:235], s[56:57], 0, v[136:137]
	s_mov_b32 m0, s55
	v_lshl_add_u64 v[236:237], s[26:27], 0, v[134:135]
	global_load_lds_dwordx4 v[234:235], off
	v_lshl_add_u64 v[234:235], s[56:57], 0, v[132:133]
	s_add_i32 m0, s55, 0x2000
	s_nop 0
	global_load_lds_dwordx4 v[234:235], off
	v_lshl_add_u64 v[234:235], s[26:27], 0, v[138:139]
	s_mov_b32 m0, s40
	s_nop 0
	global_load_lds_dwordx4 v[234:235], off
	s_mov_b32 m0, s41
	s_nop 0
	global_load_lds_dwordx4 v[236:237], off
	s_waitcnt vmcnt(8)
	s_waitcnt lgkmcnt(0)
	s_barrier
	s_waitcnt lgkmcnt(0)
	v_mfma_f32_16x16x32_bf16 v[64:67], v[146:149], v[192:195], v[64:67]
	v_mfma_f32_16x16x32_bf16 v[60:63], v[154:157], v[192:195], v[60:63]
	v_mfma_f32_16x16x32_bf16 v[56:59], v[146:149], v[208:211], v[56:59]
	v_mfma_f32_16x16x32_bf16 v[48:51], v[154:157], v[208:211], v[48:51]
	v_mfma_f32_16x16x32_bf16 v[40:43], v[146:149], v[216:219], v[40:43]
	v_mfma_f32_16x16x32_bf16 v[32:35], v[154:157], v[216:219], v[32:35]
	v_mfma_f32_16x16x32_bf16 v[24:27], v[146:149], v[224:227], v[24:27]
	v_mfma_f32_16x16x32_bf16 v[16:19], v[154:157], v[224:227], v[16:19]
	v_mfma_f32_16x16x32_bf16 v[64:67], v[150:153], v[196:199], v[64:67]
	v_mfma_f32_16x16x32_bf16 v[60:63], v[158:161], v[196:199], v[60:63]
	v_mfma_f32_16x16x32_bf16 v[56:59], v[150:153], v[212:215], v[56:59]
	v_mfma_f32_16x16x32_bf16 v[48:51], v[158:161], v[212:215], v[48:51]
	v_mfma_f32_16x16x32_bf16 v[40:43], v[150:153], v[220:223], v[40:43]
	v_mfma_f32_16x16x32_bf16 v[32:35], v[158:161], v[220:223], v[32:35]
	v_mfma_f32_16x16x32_bf16 v[24:27], v[150:153], v[228:231], v[24:27]
	v_mfma_f32_16x16x32_bf16 v[16:19], v[158:161], v[228:231], v[16:19]
	v_mfma_f32_16x16x32_bf16 v[52:55], v[162:165], v[192:195], v[52:55]
	v_mfma_f32_16x16x32_bf16 v[44:47], v[184:187], v[192:195], v[44:47]
	v_mfma_f32_16x16x32_bf16 v[36:39], v[162:165], v[208:211], v[36:39]
	v_mfma_f32_16x16x32_bf16 v[28:31], v[184:187], v[208:211], v[28:31]
	v_mfma_f32_16x16x32_bf16 v[20:23], v[162:165], v[216:219], v[20:23]
	v_mfma_f32_16x16x32_bf16 v[12:15], v[184:187], v[216:219], v[12:15]
	v_mfma_f32_16x16x32_bf16 v[8:11], v[162:165], v[224:227], v[8:11]
	v_mfma_f32_16x16x32_bf16 v[4:7], v[184:187], v[224:227], v[4:7]
	v_mfma_f32_16x16x32_bf16 v[52:55], v[180:183], v[196:199], v[52:55]
	v_mfma_f32_16x16x32_bf16 v[44:47], v[188:191], v[196:199], v[44:47]
	v_mfma_f32_16x16x32_bf16 v[36:39], v[180:183], v[212:215], v[36:39]
	v_mfma_f32_16x16x32_bf16 v[28:31], v[188:191], v[212:215], v[28:31]
	v_mfma_f32_16x16x32_bf16 v[20:23], v[180:183], v[220:223], v[20:23]
	v_mfma_f32_16x16x32_bf16 v[12:15], v[188:191], v[220:223], v[12:15]
	v_mfma_f32_16x16x32_bf16 v[8:11], v[180:183], v[228:231], v[8:11]
	v_mfma_f32_16x16x32_bf16 v[4:7], v[188:191], v[228:231], v[4:7]
	s_barrier
	s_add_i32 s55, 0, 0x18000
	v_add_u32_e32 v2, s55, v1
	s_add_i32 s56, 0, 0x1c000
	ds_read_b128 v[146:149], v2
	ds_read_b128 v[150:153], v2 offset:1024
	ds_read_b128 v[154:157], v2 offset:2048
	ds_read_b128 v[158:161], v2 offset:3072
	v_add_u32_e32 v2, s56, v1
	ds_read_b128 v[162:165], v2
	ds_read_b128 v[180:183], v2 offset:1024
	ds_read_b128 v[184:187], v2 offset:2048
	ds_read_b128 v[188:191], v2 offset:3072
	s_add_u32 s26, s26, 0x200000
	s_addc_u32 s27, s27, 0
	s_mov_b32 m0, s42
	v_lshl_add_u64 v[238:239], s[26:27], 0, v[138:139]
	ds_read_b128 v[192:195], v145 offset:32768
	ds_read_b128 v[196:199], v145 offset:33792
	ds_read_b128 v[208:211], v145 offset:34816
	ds_read_b128 v[212:215], v145 offset:35840
	ds_read_b128 v[216:219], v145 offset:36864
	ds_read_b128 v[220:223], v145 offset:37888
	ds_read_b128 v[224:227], v145 offset:38912
	ds_read_b128 v[228:231], v145 offset:39936
	global_load_lds_dwordx4 v[238:239], off
	v_lshl_add_u64 v[238:239], s[26:27], 0, v[134:135]
	s_mov_b32 m0, s43
	s_nop 0
	global_load_lds_dwordx4 v[238:239], off
	s_waitcnt vmcnt(8)
	s_waitcnt lgkmcnt(0)
	s_barrier
	s_waitcnt lgkmcnt(0)
	v_mfma_f32_16x16x32_bf16 v[128:131], v[146:149], v[192:195], v[128:131]
	v_mfma_f32_16x16x32_bf16 v[124:127], v[154:157], v[192:195], v[124:127]
	v_mfma_f32_16x16x32_bf16 v[120:123], v[146:149], v[208:211], v[120:123]
	v_mfma_f32_16x16x32_bf16 v[112:115], v[154:157], v[208:211], v[112:115]
	v_mfma_f32_16x16x32_bf16 v[104:107], v[146:149], v[216:219], v[104:107]
	v_mfma_f32_16x16x32_bf16 v[96:99], v[154:157], v[216:219], v[96:99]
	v_mfma_f32_16x16x32_bf16 v[88:91], v[146:149], v[224:227], v[88:91]
	v_mfma_f32_16x16x32_bf16 v[80:83], v[154:157], v[224:227], v[80:83]
	v_mfma_f32_16x16x32_bf16 v[128:131], v[150:153], v[196:199], v[128:131]
	v_mfma_f32_16x16x32_bf16 v[124:127], v[158:161], v[196:199], v[124:127]
	v_mfma_f32_16x16x32_bf16 v[120:123], v[150:153], v[212:215], v[120:123]
	v_mfma_f32_16x16x32_bf16 v[112:115], v[158:161], v[212:215], v[112:115]
	v_mfma_f32_16x16x32_bf16 v[104:107], v[150:153], v[220:223], v[104:107]
	v_mfma_f32_16x16x32_bf16 v[96:99], v[158:161], v[220:223], v[96:99]
	v_mfma_f32_16x16x32_bf16 v[88:91], v[150:153], v[228:231], v[88:91]
	v_mfma_f32_16x16x32_bf16 v[80:83], v[158:161], v[228:231], v[80:83]
	v_mfma_f32_16x16x32_bf16 v[116:119], v[162:165], v[192:195], v[116:119]
	v_mfma_f32_16x16x32_bf16 v[108:111], v[184:187], v[192:195], v[108:111]
	v_mfma_f32_16x16x32_bf16 v[100:103], v[162:165], v[208:211], v[100:103]
	v_mfma_f32_16x16x32_bf16 v[92:95], v[184:187], v[208:211], v[92:95]
	v_mfma_f32_16x16x32_bf16 v[84:87], v[162:165], v[216:219], v[84:87]
	v_mfma_f32_16x16x32_bf16 v[76:79], v[184:187], v[216:219], v[76:79]
	v_mfma_f32_16x16x32_bf16 v[72:75], v[162:165], v[224:227], v[72:75]
	v_mfma_f32_16x16x32_bf16 v[68:71], v[184:187], v[224:227], v[68:71]
	v_mfma_f32_16x16x32_bf16 v[116:119], v[180:183], v[196:199], v[116:119]
	v_mfma_f32_16x16x32_bf16 v[108:111], v[188:191], v[196:199], v[108:111]
	v_mfma_f32_16x16x32_bf16 v[100:103], v[180:183], v[212:215], v[100:103]
	v_mfma_f32_16x16x32_bf16 v[92:95], v[188:191], v[212:215], v[92:95]
	v_mfma_f32_16x16x32_bf16 v[84:87], v[180:183], v[220:223], v[84:87]
	v_mfma_f32_16x16x32_bf16 v[76:79], v[188:191], v[220:223], v[76:79]
	v_mfma_f32_16x16x32_bf16 v[72:75], v[180:183], v[228:231], v[72:75]
	v_mfma_f32_16x16x32_bf16 v[68:71], v[188:191], v[228:231], v[68:71]
	s_barrier
	s_add_i32 s26, s55, s35
	v_lshl_add_u64 v[166:167], v[166:167], 0, s[2:3]
	s_mov_b32 m0, s26
	ds_read_b128 v[192:195], v145 offset:49152
	ds_read_b128 v[196:199], v145 offset:50176
	ds_read_b128 v[208:211], v145 offset:51200
	ds_read_b128 v[212:215], v145 offset:52224
	ds_read_b128 v[216:219], v145 offset:53248
	ds_read_b128 v[220:223], v145 offset:54272
	ds_read_b128 v[224:227], v145 offset:55296
	ds_read_b128 v[228:231], v145 offset:56320
	global_load_lds_dwordx4 v[166:167], off
	s_add_i32 m0, s26, 0x2000
	s_add_u32 s24, s24, 0x200080
	v_lshl_add_u64 v[166:167], v[232:233], 0, s[2:3]
	s_addc_u32 s25, s25, 0
	s_add_i32 s26, s56, s35
	global_load_lds_dwordx4 v[166:167], off
	v_lshl_add_u64 v[166:167], s[24:25], 0, v[136:137]
	s_mov_b32 m0, s26
	s_nop 0
	global_load_lds_dwordx4 v[166:167], off
	v_lshl_add_u64 v[166:167], s[24:25], 0, v[132:133]
	s_add_i32 m0, s26, 0x2000
	s_nop 0
	global_load_lds_dwordx4 v[166:167], off
	v_lshl_add_u64 v[166:167], v[234:235], 0, s[2:3]
	s_mov_b32 m0, s44
	s_nop 0
	global_load_lds_dwordx4 v[166:167], off
	v_lshl_add_u64 v[166:167], v[236:237], 0, s[2:3]
	s_mov_b32 m0, s45
	s_nop 0
	global_load_lds_dwordx4 v[166:167], off
	s_add_u32 s20, s20, 0x100
	s_addc_u32 s21, s21, 0
	s_add_u32 s17, s17, 0x100
	s_addc_u32 s53, s53, 0
	s_cmp_ge_u32 s54, s51
	s_mov_b32 s24, s54
	s_waitcnt vmcnt(8)
	s_waitcnt lgkmcnt(0)
	s_barrier
	s_waitcnt lgkmcnt(0)
	v_mfma_f32_16x16x32_bf16 v[64:67], v[146:149], v[192:195], v[64:67]
	v_mfma_f32_16x16x32_bf16 v[60:63], v[154:157], v[192:195], v[60:63]
	v_mfma_f32_16x16x32_bf16 v[56:59], v[146:149], v[208:211], v[56:59]
	v_mfma_f32_16x16x32_bf16 v[48:51], v[154:157], v[208:211], v[48:51]
	v_mfma_f32_16x16x32_bf16 v[40:43], v[146:149], v[216:219], v[40:43]
	v_mfma_f32_16x16x32_bf16 v[32:35], v[154:157], v[216:219], v[32:35]
	v_mfma_f32_16x16x32_bf16 v[24:27], v[146:149], v[224:227], v[24:27]
	v_mfma_f32_16x16x32_bf16 v[16:19], v[154:157], v[224:227], v[16:19]
	v_mfma_f32_16x16x32_bf16 v[64:67], v[150:153], v[196:199], v[64:67]
	v_mfma_f32_16x16x32_bf16 v[60:63], v[158:161], v[196:199], v[60:63]
	v_mfma_f32_16x16x32_bf16 v[56:59], v[150:153], v[212:215], v[56:59]
	v_mfma_f32_16x16x32_bf16 v[48:51], v[158:161], v[212:215], v[48:51]
	v_mfma_f32_16x16x32_bf16 v[40:43], v[150:153], v[220:223], v[40:43]
	v_mfma_f32_16x16x32_bf16 v[32:35], v[158:161], v[220:223], v[32:35]
	v_mfma_f32_16x16x32_bf16 v[24:27], v[150:153], v[228:231], v[24:27]
	v_mfma_f32_16x16x32_bf16 v[16:19], v[158:161], v[228:231], v[16:19]
	v_mfma_f32_16x16x32_bf16 v[52:55], v[162:165], v[192:195], v[52:55]
	v_mfma_f32_16x16x32_bf16 v[44:47], v[184:187], v[192:195], v[44:47]
	v_mfma_f32_16x16x32_bf16 v[36:39], v[162:165], v[208:211], v[36:39]
	v_mfma_f32_16x16x32_bf16 v[28:31], v[184:187], v[208:211], v[28:31]
	v_mfma_f32_16x16x32_bf16 v[20:23], v[162:165], v[216:219], v[20:23]
	v_mfma_f32_16x16x32_bf16 v[12:15], v[184:187], v[216:219], v[12:15]
	v_mfma_f32_16x16x32_bf16 v[8:11], v[162:165], v[224:227], v[8:11]
	v_mfma_f32_16x16x32_bf16 v[4:7], v[184:187], v[224:227], v[4:7]
	v_mfma_f32_16x16x32_bf16 v[52:55], v[180:183], v[196:199], v[52:55]
	v_mfma_f32_16x16x32_bf16 v[44:47], v[188:191], v[196:199], v[44:47]
	v_mfma_f32_16x16x32_bf16 v[36:39], v[180:183], v[212:215], v[36:39]
	v_mfma_f32_16x16x32_bf16 v[28:31], v[188:191], v[212:215], v[28:31]
	v_mfma_f32_16x16x32_bf16 v[20:23], v[180:183], v[220:223], v[20:23]
	v_mfma_f32_16x16x32_bf16 v[12:15], v[188:191], v[220:223], v[12:15]
	v_mfma_f32_16x16x32_bf16 v[8:11], v[180:183], v[228:231], v[8:11]
	v_mfma_f32_16x16x32_bf16 v[4:7], v[188:191], v[228:231], v[4:7]
	s_barrier
	s_cbranch_scc0 .LBB0_1295
	s_and_b64 vcc, exec, s[8:9]
	s_cbranch_vccz .LBB0_1298
	s_barrier
